# grid barrier census: the 16 per-XCD counter loads are issued together and waited once (was 16 load+wait round trips)
# speedup vs baseline: 1.0073x; 1.0032x over previous
.LBB0_475:
	v_readlane_b32 s2, v242, 55
	v_readlane_b32 s3, v242, 56
	v_readlane_b32 s4, v242, 17
	s_nop 3
	global_load_dword v0, v1, s[2:3] sc1
	v_readlane_b32 s2, v242, 57
	v_readlane_b32 s3, v242, 58
	s_waitcnt lgkmcnt(0)
	s_nop 3
	global_load_dword v2, v1, s[2:3] sc1
	v_readlane_b32 s2, v242, 59
	v_readlane_b32 s3, v242, 60
	s_nop 4
	global_load_dword v3, v1, s[2:3] sc1
	v_readlane_b32 s2, v242, 61
	v_readlane_b32 s3, v242, 62
	s_nop 4
	global_load_dword v4, v1, s[2:3] sc1
	v_readlane_b32 s2, v242, 63
	v_readlane_b32 s3, v241, 0
	s_nop 4
	global_load_dword v5, v1, s[2:3] sc1
	v_readlane_b32 s2, v241, 1
	v_readlane_b32 s3, v241, 2
	s_nop 4
	global_load_dword v6, v1, s[2:3] sc1
	v_readlane_b32 s2, v241, 3
	v_readlane_b32 s3, v241, 4
	s_nop 4
	global_load_dword v7, v1, s[2:3] sc1
	v_readlane_b32 s2, v241, 5
	v_readlane_b32 s3, v241, 6
	s_nop 4
	global_load_dword v8, v1, s[2:3] sc1
	v_readlane_b32 s2, v241, 7
	v_readlane_b32 s3, v241, 8
	s_nop 4
	global_load_dword v9, v1, s[2:3] sc1
	v_readlane_b32 s2, v241, 9
	v_readlane_b32 s3, v241, 10
	s_nop 4
	global_load_dword v10, v1, s[2:3] sc1
	v_readlane_b32 s2, v241, 11
	v_readlane_b32 s3, v241, 12
	s_nop 4
	global_load_dword v11, v1, s[2:3] sc1
	v_readlane_b32 s2, v241, 13
	v_readlane_b32 s3, v241, 14
	s_nop 4
	global_load_dword v12, v1, s[2:3] sc1
	v_readlane_b32 s2, v241, 15
	v_readlane_b32 s3, v241, 16
	s_nop 4
	global_load_dword v13, v1, s[2:3] sc1
	v_readlane_b32 s2, v241, 17
	v_readlane_b32 s3, v241, 18
	s_nop 4
	global_load_dword v14, v1, s[2:3] sc1
	v_readlane_b32 s2, v241, 19
	v_readlane_b32 s3, v241, 20
	s_nop 4
	global_load_dword v15, v1, s[2:3] sc1
	v_readlane_b32 s2, v241, 21
	v_readlane_b32 s3, v241, 22
	s_nop 4
	global_load_dword v16, v1, s[2:3] sc1
	s_mov_b64 s[2:3], -1
	s_waitcnt vmcnt(0)
	v_add_u32_e32 v17, v2, v0
	v_add_u32_e32 v17, v17, v3
	v_add_u32_e32 v17, v17, v4
	v_add_u32_e32 v17, v17, v5
	v_add_u32_e32 v17, v17, v6
	v_add_u32_e32 v17, v17, v7
	v_add_u32_e32 v17, v17, v8
	v_add_u32_e32 v17, v17, v9
	v_add_u32_e32 v17, v17, v10
	v_add_u32_e32 v17, v17, v11
	v_add_u32_e32 v17, v17, v12
	v_add_u32_e32 v17, v17, v13
	v_add_u32_e32 v17, v17, v14
	v_add_u32_e32 v17, v17, v15
	v_add_u32_e32 v17, v17, v16
	v_cmp_eq_u32_e32 vcc, s4, v17
	s_mov_b64 s[4:5], -1
	s_cbranch_vccnz .LBB0_474
	s_and_b32 s2, s9, 0xff
	s_cmp_eq_u32 s2, 0
	s_mov_b64 s[2:3], -1
	s_mov_b64 s[6:7], -1
	s_sleep 1
	s_cbranch_scc0 .LBB0_479
	v_readlane_b32 s2, v242, 53
	v_readlane_b32 s3, v242, 54
	s_nop 4
	global_load_dword v17, v1, s[2:3] sc1
	s_waitcnt vmcnt(0)
	v_cmp_eq_u32_e32 vcc, 0, v17
	s_cbranch_vccnz .LBB0_481
	s_mov_b64 s[6:7], 0
	s_mov_b64 s[2:3], -1
